# P6 gMLP chunk loop: LayerNorm statistics and v-column loads prefetched one chunk ahead with counted waits; ln gain/bias hoisted out of the loop
# baseline (speedup 1.0000x reference)
; #define LAS __attribute__((address_space(3)))
; __device__ __forceinline__ unsigned pk2(float lo, float hi) { const f32x2 v = {lo, hi}; const bf16x2_t b = __builtin_convertvector(v, bf16x2_t); return __builtin_bit_cast(unsigned, b); }
; __device__ __forceinline__ void gmlp_phase(const Ctx& C) {
;     ...
;         for (int e = tid; e < 128 * 64; e += NTHR) {
;             const int t = e >> 6, s2 = (e & 63) * 2;
;             const f32x2 wv = *(const f32x2*)(w_s + ((size_t)hh * 128 + t) * 128 + s2);
;             const unsigned pk = pk2(s2 <= t ? wv.x : 0.f, (s2 + 1) <= t ? wv.y : 0.f);
;             *(LAS unsigned*)(Aw + t * AS + s2) = pk;
;         }
;         for (int ch = (C.G >= 8 ? slot : C.bid); ch < 128; ch += (C.G >= 8 ? nslots : C.G)) {
;             const int tok0 = ch * 128;
;             const int dd = tid & 63;
;             bf16_t vr[16], ur[4][4]; float bsr[4]; f32x4 sta = (f32x4){0.f, 0.f, 0.f, 0.f}, stb = sta, stc = sta, std_ = sta;
; #pragma unroll
;             for (int i = 0; i < 16; ++i) vr[i] = zg[(size_t)(tok0 + (tid >> 6) + 8 * i) * 1024 + 512 + hh * 64 + dd];
; #pragma unroll
;             for (int n = 0; n < 4; ++n)
; #pragma unroll
;                 for (int j = 0; j < 4; ++j) ur[n][j] = zg[(size_t)(tok0 + w * 16 + 4 * q + j) * 1024 + hh * 64 + n * 16 + l15];
; #pragma unroll
;             for (int j = 0; j < 4; ++j) bsr[j] = b_s[hh * 128 + w * 16 + 4 * q + j];
;             if (tid < 128) { const f32x4* p = (const f32x4*)(lnst + (size_t)(tok0 + tid) * 16); sta = p[0]; stb = p[1]; stc = p[2]; std_ = p[3]; }
.LBB0_940:
	global_load_dwordx2 v[12:13], v[4:5], off
	v_cmp_le_u32_e32 vcc, v2, v11
	v_cmp_lt_u32_e64 s[6:7], v2, v11
	v_add_u32_e32 v10, 0x200, v10
	v_cmp_lt_u32_e64 s[8:9], s4, v10
	v_lshl_add_u64 v[4:5], v[4:5], 0, s[12:13]
	v_add_u32_e32 v11, 8, v11
	s_or_b64 s[10:11], s[8:9], s[10:11]
	s_waitcnt vmcnt(0)
	v_cndmask_b32_e32 v12, 0, v12, vcc
	v_cndmask_b32_e64 v13, 0, v13, s[6:7]
	v_cvt_pk_bf16_f32 v12, v12, v13
	ds_write_b32 v9, v12
	v_add_u32_e32 v9, 0x880, v9
	s_andn2_b64 exec, exec, s[10:11]
	s_cbranch_execnz .LBB0_940
	s_or_b64 exec, exec, s[10:11]
	s_cmpk_gt_u32 s3, 0x3ff
	s_cbranch_scc1 .LBB0_952
	s_add_u32 s4, s26, 0x3800000
	s_addc_u32 s5, s27, 0
	s_lshl_b32 s3, s80, 4
	v_lshrrev_b32_e32 v4, 2, v193
	v_and_b32_e32 v9, 48, v193
	v_and_or_b32 v46, v4, 12, s3
	v_lshlrev_b32_e32 v22, 1, v7
	v_or_b32_e32 v7, s3, v7
	v_add_u32_e32 v10, 0, v9
	s_movk_i32 s3, 0x110
	v_mad_u64_u32 v[24:25], s[10:11], v7, s3, v[10:11]
	s_cmpk_gt_u32 s55, 0x7f
	s_cselect_b64 s[10:11], -1, 0
	s_cmpk_gt_u32 s55, 0xff
	s_cselect_b64 s[12:13], -1, 0
	s_cmpk_gt_u32 s55, 0x17f
	s_cselect_b64 s[16:17], -1, 0
	s_add_u32 s18, s26, 0xf500000
	v_mov_b32_e32 v23, 0
	s_addc_u32 s19, s27, 0
	s_lshl_b32 s8, s2, 7
	s_mov_b32 s9, 0
	v_lshl_add_u64 v[4:5], s[4:5], 0, v[22:23]
	v_lshl_or_b32 v8, s2, 8, v8
	v_readlane_b32 s36, v254, 42
	s_add_u32 s2, s26, s8
	v_lshl_add_u64 v[26:27], v[4:5], 0, s[8:9]
	v_add_u32_e32 v4, s8, v46
	v_readlane_b32 s48, v254, 54
	v_readlane_b32 s49, v254, 55
	s_addc_u32 s3, s27, 0
	v_mov_b32_e32 v5, v23
	v_lshl_add_u64 v[32:33], v[4:5], 2, s[48:49]
	v_lshl_add_u64 v[4:5], s[2:3], 0, v[22:23]
	s_mov_b64 s[2:3], 0x5800400
	v_lshlrev_b32_e32 v7, 1, v1
	v_lshl_add_u64 v[34:35], v[4:5], 0, s[2:3]
	s_add_u32 s2, s4, s8
	s_movk_i32 s6, 0x80
	v_add3_u32 v48, 0, v3, v7
	v_mov_b32_e32 v9, v23
	v_readlane_b32 s42, v254, 48
	v_readlane_b32 s43, v254, 49
	v_readlane_b32 s44, v254, 50
	v_readlane_b32 s45, v254, 51
	s_addc_u32 s3, s5, 0
	v_mov_b32_e32 v3, v23
	v_cmp_gt_u32_e64 s[6:7], s6, v0
	v_lshl_add_u32 v47, v0, 2, 0
	v_lshl_add_u32 v25, v1, 2, 0
	v_lshl_add_u64 v[28:29], s[42:43], 0, v[8:9]
	v_lshl_add_u64 v[30:31], s[44:45], 0, v[8:9]
	v_lshl_add_u64 v[36:37], s[2:3], 0, v[2:3]
	s_lshl_b32 s2, s1, 7
	s_lshl_b32 s3, s0, 7
	s_mov_b32 s4, 0x3b000000
	s_mov_b32 s5, 0xf800000
	v_mov_b32_e32 v49, 0x260
	v_add_u32_e32 v50, v10, v6
	v_mov_b32_e32 v51, v0
	v_readlane_b32 s37, v254, 43
	v_readlane_b32 s38, v254, 44
	v_readlane_b32 s39, v254, 45
	v_readlane_b32 s40, v254, 46
	v_readlane_b32 s41, v254, 47
	v_readlane_b32 s46, v254, 52
	v_readlane_b32 s47, v254, 53
	v_readlane_b32 s50, v254, 56
	v_readlane_b32 s51, v254, 57
	s_mov_b64 s[56:57], 0x4000
	global_load_dword v132, v[28:29], off
	global_load_dword v133, v[30:31], off
	s_and_saveexec_b64 s[8:9], s[6:7]
	s_cbranch_execz .Lmy_gp0_skip
	v_add_u32_e32 v140, s2, v51
	v_mov_b32_e32 v141, 0
	v_lshlrev_b64 v[140:141], 6, v[140:141]
	v_lshl_add_u64 v[140:141], s[18:19], 0, v[140:141]
	global_load_dwordx4 v[116:119], v[140:141], off offset:48
	global_load_dwordx4 v[120:123], v[140:141], off offset:32
	global_load_dwordx4 v[124:127], v[140:141], off offset:16
	global_load_dwordx4 v[128:131], v[140:141], off
.Lmy_gp0_skip:
	s_or_b64 exec, exec, s[8:9]
	v_add_u32_e32 v134, s2, v1
	v_mov_b32_e32 v135, 0
	v_lshlrev_b64 v[136:137], 11, v[134:135]
	v_lshl_add_u64 v[136:137], v[36:37], 0, v[136:137]
	global_load_ushort v100, v[136:137], off offset:1024
	v_lshl_add_u64 v[138:139], v[136:137], 0, s[56:57]
	global_load_ushort v101, v[138:139], off offset:1024
	v_lshl_add_u64 v[136:137], v[138:139], 0, s[56:57]
	global_load_ushort v102, v[136:137], off offset:1024
	v_lshl_add_u64 v[138:139], v[136:137], 0, s[56:57]
	global_load_ushort v103, v[138:139], off offset:1024
	v_lshl_add_u64 v[136:137], v[138:139], 0, s[56:57]
	global_load_ushort v104, v[136:137], off offset:1024
	v_lshl_add_u64 v[138:139], v[136:137], 0, s[56:57]
	global_load_ushort v105, v[138:139], off offset:1024
	v_lshl_add_u64 v[136:137], v[138:139], 0, s[56:57]
	global_load_ushort v106, v[136:137], off offset:1024
	v_lshl_add_u64 v[138:139], v[136:137], 0, s[56:57]
	global_load_ushort v107, v[138:139], off offset:1024
	v_lshl_add_u64 v[136:137], v[138:139], 0, s[56:57]
	global_load_ushort v108, v[136:137], off offset:1024
	v_lshl_add_u64 v[138:139], v[136:137], 0, s[56:57]
	global_load_ushort v109, v[138:139], off offset:1024
	v_lshl_add_u64 v[136:137], v[138:139], 0, s[56:57]
	global_load_ushort v110, v[136:137], off offset:1024
	v_lshl_add_u64 v[138:139], v[136:137], 0, s[56:57]
	global_load_ushort v111, v[138:139], off offset:1024
	v_lshl_add_u64 v[136:137], v[138:139], 0, s[56:57]
	global_load_ushort v112, v[136:137], off offset:1024
	v_lshl_add_u64 v[138:139], v[136:137], 0, s[56:57]
	global_load_ushort v113, v[138:139], off offset:1024
	v_lshl_add_u64 v[136:137], v[138:139], 0, s[56:57]
	global_load_ushort v114, v[136:137], off offset:1024
	v_lshl_add_u64 v[138:139], v[136:137], 0, s[56:57]
	global_load_ushort v115, v[138:139], off offset:1024
	s_branch .LBB0_944
; __device__ __forceinline__ void gmlp_phase(const Ctx& C) {
;     ...
;             bf16_t vr[16], ur[4][4]; float bsr[4]; f32x4 sta = (f32x4){0.f, 0.f, 0.f, 0.f}, stb = sta, stc = sta, std_ = sta;
; #pragma unroll
;             for (int i = 0; i < 16; ++i) vr[i] = zg[(size_t)(tok0 + (tid >> 6) + 8 * i) * 1024 + 512 + hh * 64 + dd];
; #pragma unroll
;             for (int n = 0; n < 4; ++n)
; #pragma unroll
;                 for (int j = 0; j < 4; ++j) ur[n][j] = zg[(size_t)(tok0 + w * 16 + 4 * q + j) * 1024 + hh * 64 + n * 16 + l15];
; #pragma unroll
;             for (int j = 0; j < 4; ++j) bsr[j] = b_s[hh * 128 + w * 16 + 4 * q + j];
;             if (tid < 128) { const f32x4* p = (const f32x4*)(lnst + (size_t)(tok0 + tid) * 16); sta = p[0]; stb = p[1]; stc = p[2]; std_ = p[3]; }
;             __syncthreads();
;             if (tid < 128) {
;                 const float s1 = ((sta[0] + sta[2]) + (stb[0] + stb[2])) + ((stc[0] + stc[2]) + (std_[0] + std_[2]));
;                 const float s2 = ((sta[1] + sta[3]) + (stb[1] + stb[3])) + ((stc[1] + stc[3]) + (std_[1] + std_[3]));
;                 const float mean = s1 * (1.0f / 512.0f); const float var = fmaxf(s2 * (1.0f / 512.0f) - mean * mean, 0.f);
;                 st[tid] = mean; st[128 + tid] = 1.0f / sqrtf(var + 1e-5f);
;             }
;             __syncthreads();
;             {
;                 const float gg = ln_g[hh * 64 + dd], bb = ln_b[hh * 64 + dd];
; #pragma unroll
;                 for (int i = 0; i < 16; ++i) { const int s_ = (tid >> 6) + 8 * i;
;                     vT[dd * AS + s_] = f2bf((bf2f(vr[i]) - st[s_]) * st[128 + s_] * gg + bb); }
;             }
;             __syncthreads();
;             f32x4 acc[4];
; #pragma unroll
;             for (int n = 0; n < 4; ++n) acc[n] = (f32x4){0.f, 0.f, 0.f, 0.f};
;             for (int ks = 0; ks < 4; ++ks) {
;                 if (ks * 32 > w * 16 + 15) break;
;                 const bf16x8 a = *(const LAS bf16x8*)(Aw + (w * 16 + l15) * AS + ks * 32 + q * 8);
; #pragma unroll
;                 for (int n = 0; n < 4; ++n) {
;                     const bf16x8 b = *(const LAS bf16x8*)(vT + (n * 16 + l15) * AS + ks * 32 + q * 8);
;                     acc[n] = __builtin_amdgcn_mfma_f32_16x16x32_bf16(a, b, acc[n], 0, 0, 0);
;                 }
;             }
; #pragma unroll
;             for (int n = 0; n < 4; ++n)
; #pragma unroll
.LBB0_943:
	s_waitcnt vmcnt(16)
	v_lshlrev_b32_e32 v22, 16, v66
	v_add_f32_e32 v18, v2, v18
	v_mul_f32_e32 v18, v18, v22
	v_cvt_pk_bf16_f32 v18, v18, s0
	v_lshl_add_u64 v[38:39], v[34:35], 0, v[38:39]
	global_store_short v[38:39], v18, off
	v_lshlrev_b32_e32 v18, 16, v64
	v_add_f32_e32 v19, v3, v19
	v_mul_f32_e32 v18, v19, v18
	v_cvt_pk_bf16_f32 v22, v18, s0
	v_lshl_add_u64 v[18:19], v[34:35], 0, v[40:41]
	global_store_short v[18:19], v22, off
	v_lshlrev_b32_e32 v22, 16, v67
	v_add_f32_e32 v20, v4, v20
	v_mul_f32_e32 v20, v20, v22
	v_cvt_pk_bf16_f32 v20, v20, s0
	v_lshl_add_u64 v[40:41], v[34:35], 0, v[42:43]
	global_store_short v[40:41], v20, off
	v_lshlrev_b32_e32 v20, 16, v65
	v_add_f32_e32 v21, v5, v21
	v_mul_f32_e32 v20, v21, v20
	v_cvt_pk_bf16_f32 v22, v20, s0
	v_lshl_add_u64 v[20:21], v[34:35], 0, v[44:45]
	global_store_short v[20:21], v22, off
	v_lshlrev_b32_e32 v22, 16, v62
	v_add_f32_e32 v14, v2, v14
	v_mul_f32_e32 v14, v14, v22
	v_cvt_pk_bf16_f32 v14, v14, s0
	global_store_short v[38:39], v14, off offset:32
	v_lshlrev_b32_e32 v14, 16, v60
	v_add_f32_e32 v15, v3, v15
	v_mul_f32_e32 v14, v15, v14
	v_cvt_pk_bf16_f32 v14, v14, s0
	global_store_short v[18:19], v14, off offset:32
	v_lshlrev_b32_e32 v14, 16, v63
	v_add_f32_e32 v15, v4, v16
	v_mul_f32_e32 v14, v15, v14
	v_cvt_pk_bf16_f32 v14, v14, s0
	global_store_short v[40:41], v14, off offset:32
	v_lshlrev_b32_e32 v14, 16, v61
	v_add_f32_e32 v15, v5, v17
	v_mul_f32_e32 v14, v15, v14
	v_cvt_pk_bf16_f32 v14, v14, s0
	global_store_short v[20:21], v14, off offset:32
	v_lshlrev_b32_e32 v14, 16, v58
	v_add_f32_e32 v10, v2, v10
	v_mul_f32_e32 v10, v10, v14
	v_cvt_pk_bf16_f32 v10, v10, s0
	global_store_short v[38:39], v10, off offset:64
	v_lshlrev_b32_e32 v10, 16, v56
	v_add_f32_e32 v11, v3, v11
	v_mul_f32_e32 v10, v11, v10
	v_cvt_pk_bf16_f32 v10, v10, s0
	global_store_short v[18:19], v10, off offset:64
	v_lshlrev_b32_e32 v10, 16, v59
	v_add_f32_e32 v11, v4, v12
	v_mul_f32_e32 v10, v11, v10
	v_cvt_pk_bf16_f32 v10, v10, s0
	global_store_short v[40:41], v10, off offset:64
	v_lshlrev_b32_e32 v10, 16, v57
	v_add_f32_e32 v11, v5, v13
	v_mul_f32_e32 v10, v11, v10
	v_cvt_pk_bf16_f32 v10, v10, s0
	global_store_short v[20:21], v10, off offset:64
	v_lshlrev_b32_e32 v10, 16, v55
	v_add_f32_e32 v2, v2, v6
	v_mul_f32_e32 v2, v2, v10
	v_cvt_pk_bf16_f32 v2, v2, s0
	global_store_short v[38:39], v2, off offset:96
	v_lshlrev_b32_e32 v2, 16, v53
	v_add_f32_e32 v3, v3, v7
	v_mul_f32_e32 v2, v3, v2
	v_cvt_pk_bf16_f32 v2, v2, s0
	global_store_short v[18:19], v2, off offset:96
	v_lshlrev_b32_e32 v2, 16, v54
	v_add_f32_e32 v3, v4, v8
	v_mul_f32_e32 v2, v3, v2
	v_cvt_pk_bf16_f32 v2, v2, s0
	global_store_short v[40:41], v2, off offset:96
	v_lshlrev_b32_e32 v2, 16, v52
	v_add_f32_e32 v3, v5, v9
	v_mul_f32_e32 v2, v3, v2
	s_add_i32 s1, s1, s0
	v_cvt_pk_bf16_f32 v2, v2, s0
	v_add_u32_e32 v51, s3, v51
	v_add_u32_e32 v1, s3, v1
	s_cmpk_gt_u32 s1, 0x7f
	v_add_u32_e32 v46, s3, v46
	global_store_short v[20:21], v2, off offset:96
	s_cbranch_scc1 .LBB0_952
.LBB0_944:
	v_add_u32_e32 v2, s2, v46
	v_ashrrev_i32_e32 v3, 31, v2
	v_lshlrev_b64 v[38:39], 11, v[2:3]
	v_add_u32_e32 v6, 1, v2
	v_add_u32_e32 v8, 2, v2
	v_add_u32_e32 v2, 3, v2
	v_ashrrev_i32_e32 v3, 31, v2
	v_ashrrev_i32_e32 v7, 31, v6
	v_ashrrev_i32_e32 v9, 31, v8
	v_lshlrev_b64 v[44:45], 11, v[2:3]
	v_lshl_add_u64 v[4:5], v[26:27], 0, v[38:39]
	v_lshlrev_b64 v[40:41], 11, v[6:7]
	v_lshlrev_b64 v[42:43], 11, v[8:9]
	v_lshl_add_u64 v[2:3], v[26:27], 0, v[44:45]
	v_lshl_add_u64 v[6:7], v[26:27], 0, v[40:41]
	v_lshl_add_u64 v[8:9], v[26:27], 0, v[42:43]
	global_load_ushort v66, v[4:5], off
	global_load_ushort v64, v[6:7], off
	global_load_ushort v62, v[4:5], off offset:32
	global_load_ushort v60, v[6:7], off offset:32
	global_load_ushort v58, v[4:5], off offset:64
	global_load_ushort v56, v[6:7], off offset:64
	global_load_ushort v53, v[6:7], off offset:96
	global_load_ushort v55, v[4:5], off offset:96
	global_load_ushort v67, v[8:9], off
	global_load_ushort v65, v[2:3], off
	global_load_ushort v63, v[8:9], off offset:32
	global_load_ushort v61, v[2:3], off offset:32
	global_load_ushort v59, v[8:9], off offset:64
	global_load_ushort v57, v[2:3], off offset:64
	global_load_ushort v52, v[2:3], off offset:96
	global_load_ushort v54, v[8:9], off offset:96
	s_nop 0
	global_load_dwordx4 v[2:5], v[32:33], off
	s_waitcnt lgkmcnt(0)
	s_barrier
	s_and_saveexec_b64 s[20:21], s[6:7]
	s_cbranch_execz .LBB0_948
	s_waitcnt vmcnt(33)
	v_add_f32_e32 v18, v128, v130
	v_add_f32_e32 v14, v124, v126
	v_add_f32_e32 v10, v120, v122
	v_add_f32_e32 v6, v116, v118
	v_add_f32_e32 v14, v14, v18
	v_add_f32_e32 v6, v6, v10
	v_add_f32_e32 v8, v129, v131
	v_add_f32_e32 v10, v125, v127
	v_add_f32_e32 v6, v6, v14
	v_add_f32_e32 v8, v10, v8
	v_add_f32_e32 v10, v121, v123
	v_add_f32_e32 v7, v117, v119
	v_add_f32_e32 v7, v7, v10
	v_mul_f32_e32 v6, 0x3b000000, v6
	v_add_f32_e32 v7, v7, v8
	v_mul_f32_e32 v8, v6, v6
	v_fma_f32 v7, v7, s4, -v8
	v_max_f32_e32 v7, 0, v7
	v_add_f32_e32 v7, 0x3727c5ac, v7
	v_mul_f32_e32 v8, 0x4f800000, v7
	v_cmp_gt_f32_e32 vcc, s5, v7
	s_nop 1
	v_cndmask_b32_e32 v7, v7, v8, vcc
	v_sqrt_f32_e32 v8, v7
	s_nop 0
	v_add_u32_e32 v9, -1, v8
	v_fma_f32 v10, -v9, v8, v7
	v_cmp_ge_f32_e64 s[8:9], 0, v10
	v_add_u32_e32 v10, 1, v8
	s_nop 0
	v_cndmask_b32_e64 v9, v8, v9, s[8:9]
	v_fma_f32 v8, -v10, v8, v7
	v_cmp_lt_f32_e64 s[8:9], 0, v8
	s_nop 1
	v_cndmask_b32_e64 v8, v9, v10, s[8:9]
	v_mul_f32_e32 v9, 0x37800000, v8
	v_cndmask_b32_e32 v8, v8, v9, vcc
	v_cmp_class_f32_e32 vcc, v7, v49
	s_nop 1
	v_cndmask_b32_e32 v7, v8, v7, vcc
	v_div_scale_f32 v8, s[8:9], v7, v7, 1.0
	v_rcp_f32_e32 v9, v8
	s_nop 0
	v_fma_f32 v10, -v8, v9, 1.0
	v_fmac_f32_e32 v9, v10, v9
	v_div_scale_f32 v10, vcc, 1.0, v7, 1.0
	v_mul_f32_e32 v11, v10, v9
	v_fma_f32 v12, -v8, v11, v10
	v_fmac_f32_e32 v11, v12, v9
	v_fma_f32 v8, -v8, v11, v10
	v_div_fmas_f32 v8, v8, v9, v11
	v_div_fixup_f32 v7, v8, v7, 1.0
	ds_write2st64_b32 v47, v6, v7 offset0:204 offset1:206
; __device__ __forceinline__ float bf2f(bf16_t b) { return __uint_as_float(((unsigned)b) << 16); }
; __device__ __forceinline__ bf16_t f2bf(float f) { return (bf16_t)(pk2(f, 0.f) & 0xffffu); }
; __device__ __forceinline__ void gmlp_phase(const Ctx& C) {
;     ...
;             if (tid < 128) { const f32x4* p = (const f32x4*)(lnst + (size_t)(tok0 + tid) * 16); sta = p[0]; stb = p[1]; stc = p[2]; std_ = p[3]; }
;             __syncthreads();
;             if (tid < 128) {
;                 const float s1 = ((sta[0] + sta[2]) + (stb[0] + stb[2])) + ((stc[0] + stc[2]) + (std_[0] + std_[2]));
;                 const float s2 = ((sta[1] + sta[3]) + (stb[1] + stb[3])) + ((stc[1] + stc[3]) + (std_[1] + std_[3]));
;                 const float mean = s1 * (1.0f / 512.0f); const float var = fmaxf(s2 * (1.0f / 512.0f) - mean * mean, 0.f);
;                 st[tid] = mean; st[128 + tid] = 1.0f / sqrtf(var + 1e-5f);
;             }
;             __syncthreads();
;             {
;                 const float gg = ln_g[hh * 64 + dd], bb = ln_b[hh * 64 + dd];
; #pragma unroll
;                 for (int i = 0; i < 16; ++i) { const int s_ = (tid >> 6) + 8 * i;
;                     vT[dd * AS + s_] = f2bf((bf2f(vr[i]) - st[s_]) * st[128 + s_] * gg + bb); }
;             }
;             __syncthreads();
.LBB0_948:
	s_or_b64 exec, exec, s[20:21]
	s_waitcnt lgkmcnt(0)
	s_barrier
	s_waitcnt vmcnt(17)
	v_add_u32_e32 v85, 0xcc00, v25
	v_lshlrev_b32_e32 v86, 16, v101
	v_lshlrev_b32_e32 v87, 16, v102
	v_lshlrev_b32_e32 v88, 16, v103
	v_lshlrev_b32_e32 v89, 16, v104
	v_lshlrev_b32_e32 v90, 16, v105
	v_lshlrev_b32_e32 v91, 16, v106
	v_lshlrev_b32_e32 v92, 16, v109
	v_lshlrev_b32_e32 v93, 16, v110
	ds_read2_b32 v[6:7], v85 offset1:8
	ds_read2_b32 v[8:9], v85 offset0:128 offset1:136
	ds_read2_b32 v[10:11], v85 offset0:16 offset1:24
	ds_read2_b32 v[12:13], v85 offset0:144 offset1:152
	ds_read2_b32 v[14:15], v85 offset0:32 offset1:40
	ds_read2_b32 v[16:17], v85 offset0:160 offset1:168
	ds_read2_b32 v[18:19], v85 offset0:48 offset1:56
	ds_read2_b32 v[20:21], v85 offset0:176 offset1:184
	ds_read2_b32 v[74:75], v85 offset0:64 offset1:72
	ds_read2_b32 v[76:77], v85 offset0:192 offset1:200
	ds_read2_b32 v[78:79], v85 offset0:80 offset1:88
	ds_read2_b32 v[80:81], v85 offset0:208 offset1:216
	v_lshlrev_b32_e32 v83, 16, v100
	v_lshlrev_b32_e32 v73, 16, v107
	v_lshlrev_b32_e32 v82, 16, v108
	s_waitcnt lgkmcnt(11)
	v_sub_f32_e32 v6, v83, v6
	v_sub_f32_e32 v7, v86, v7
	s_waitcnt lgkmcnt(9)
	v_sub_f32_e32 v10, v87, v10
	v_sub_f32_e32 v11, v88, v11
	s_waitcnt lgkmcnt(7)
	v_sub_f32_e32 v14, v89, v14
	v_sub_f32_e32 v15, v90, v15
	s_waitcnt lgkmcnt(5)
	v_sub_f32_e32 v18, v91, v18
	v_sub_f32_e32 v19, v73, v19
	s_waitcnt lgkmcnt(3)
	v_sub_f32_e32 v73, v82, v74
	v_sub_f32_e32 v74, v92, v75
	s_waitcnt lgkmcnt(1)
	v_sub_f32_e32 v75, v93, v78
	v_mul_f32_e32 v6, v6, v8
	v_mul_f32_e32 v7, v7, v9
	v_mul_f32_e32 v8, v10, v12
	v_mul_f32_e32 v9, v11, v13
	v_mul_f32_e32 v10, v14, v16
	v_mul_f32_e32 v11, v15, v17
	v_mul_f32_e32 v12, v18, v20
	v_mul_f32_e32 v13, v19, v21
	v_mul_f32_e32 v14, v73, v76
	v_mul_f32_e32 v15, v74, v77
	s_waitcnt lgkmcnt(0)
	v_mul_f32_e32 v16, v75, v80
	s_andn2_b64 vcc, exec, s[10:11]
	v_fma_f32 v6, v132, v6, v133
	v_fma_f32 v7, v132, v7, v133
	v_fma_f32 v8, v132, v8, v133
	v_fma_f32 v9, v132, v9, v133
	v_fma_f32 v10, v132, v10, v133
	v_fma_f32 v11, v132, v11, v133
	v_fma_f32 v12, v132, v12, v133
	v_fma_f32 v13, v132, v13, v133
	v_fma_f32 v14, v132, v14, v133
	v_fma_f32 v15, v132, v15, v133
	v_fma_f32 v16, v132, v16, v133
	v_cvt_pk_bf16_f32 v6, v6, s0
	v_cvt_pk_bf16_f32 v7, v7, s0
	v_cvt_pk_bf16_f32 v8, v8, s0
	v_cvt_pk_bf16_f32 v9, v9, s0
	v_cvt_pk_bf16_f32 v10, v10, s0
	v_cvt_pk_bf16_f32 v11, v11, s0
	v_cvt_pk_bf16_f32 v12, v12, s0
	v_cvt_pk_bf16_f32 v13, v13, s0
	v_cvt_pk_bf16_f32 v14, v14, s0
	v_cvt_pk_bf16_f32 v15, v15, s0
	v_cvt_pk_bf16_f32 v16, v16, s0
	ds_write_b16 v48, v6 offset:34816
	ds_write_b16 v48, v7 offset:34832
	ds_write_b16 v48, v8 offset:34848
	ds_write_b16 v48, v9 offset:34864
	ds_write_b16 v48, v10 offset:34880
	ds_write_b16 v48, v11 offset:34896
	ds_write_b16 v48, v12 offset:34912
	ds_write_b16 v48, v13 offset:34928
	ds_write_b16 v48, v14 offset:34944
	ds_write_b16 v48, v15 offset:34960
	ds_write_b16 v48, v16 offset:34976
	v_lshlrev_b32_e32 v6, 16, v111
	v_sub_f32_e32 v6, v6, v79
	v_mul_f32_e32 v6, v6, v81
	v_fma_f32 v10, v132, v6, v133
	ds_read2_b32 v[6:7], v85 offset0:96 offset1:104
	ds_read2_b32 v[8:9], v85 offset0:224 offset1:232
	v_cvt_pk_bf16_f32 v10, v10, s0
	ds_write_b16 v48, v10 offset:34992
	v_lshlrev_b32_e32 v10, 16, v112
	s_waitcnt lgkmcnt(2)
	v_sub_f32_e32 v6, v10, v6
	s_waitcnt lgkmcnt(1)
	v_mul_f32_e32 v6, v6, v8
	v_fma_f32 v6, v132, v6, v133
	v_cvt_pk_bf16_f32 v6, v6, s0
	ds_write_b16 v48, v6 offset:35008
	v_lshlrev_b32_e32 v6, 16, v113
	v_sub_f32_e32 v6, v6, v7
	v_mul_f32_e32 v6, v6, v9
	v_fma_f32 v10, v132, v6, v133
	ds_read2_b32 v[6:7], v85 offset0:112 offset1:120
	ds_read2_b32 v[8:9], v85 offset0:240 offset1:248
	v_cvt_pk_bf16_f32 v10, v10, s0
	ds_write_b16 v48, v10 offset:35024
	v_lshlrev_b32_e32 v10, 16, v114
	s_waitcnt lgkmcnt(2)
	v_sub_f32_e32 v6, v10, v6
	s_waitcnt lgkmcnt(1)
	v_mul_f32_e32 v6, v6, v8
	v_fma_f32 v6, v132, v6, v133
	v_cvt_pk_bf16_f32 v6, v6, s0
	ds_write_b16 v48, v6 offset:35040
	v_lshlrev_b32_e32 v6, 16, v115
	v_sub_f32_e32 v6, v6, v7
	v_mul_f32_e32 v6, v6, v9
	v_fma_f32 v6, v132, v6, v133
	v_cvt_pk_bf16_f32 v6, v6, s0
	ds_write_b16 v48, v6 offset:35056
	s_waitcnt lgkmcnt(0)
	s_barrier
	s_add_i32 s59, s1, s0
	s_cmpk_gt_u32 s59, 0x7f
	s_cselect_b32 s58, 0, s3
	s_and_saveexec_b64 s[8:9], s[6:7]
	s_cbranch_execz .Lmy_gpn_skip
	v_add_u32_e32 v140, s2, v51
	v_add_u32_e32 v140, s58, v140
	v_mov_b32_e32 v141, 0
	v_lshlrev_b64 v[140:141], 6, v[140:141]
	v_lshl_add_u64 v[140:141], s[18:19], 0, v[140:141]
	global_load_dwordx4 v[116:119], v[140:141], off offset:48
	global_load_dwordx4 v[120:123], v[140:141], off offset:32
	global_load_dwordx4 v[124:127], v[140:141], off offset:16
	global_load_dwordx4 v[128:131], v[140:141], off
; #define LAS __attribute__((address_space(3)))
; __device__ __forceinline__ void gmlp_phase(const Ctx& C) {
;     ...
;             for (int i = 0; i < 16; ++i) vr[i] = zg[(size_t)(tok0 + (tid >> 6) + 8 * i) * 1024 + 512 + hh * 64 + dd];
; #pragma unroll
;             for (int n = 0; n < 4; ++n)
; #pragma unroll
;                 for (int j = 0; j < 4; ++j) ur[n][j] = zg[(size_t)(tok0 + w * 16 + 4 * q + j) * 1024 + hh * 64 + n * 16 + l15];
;     ...
;             f32x4 acc[4];
; #pragma unroll
;             for (int n = 0; n < 4; ++n) acc[n] = (f32x4){0.f, 0.f, 0.f, 0.f};
;             for (int ks = 0; ks < 4; ++ks) {
;                 if (ks * 32 > w * 16 + 15) break;
;                 const bf16x8 a = *(const LAS bf16x8*)(Aw + (w * 16 + l15) * AS + ks * 32 + q * 8);
; #pragma unroll
;                 for (int n = 0; n < 4; ++n) {
;                     const bf16x8 b = *(const LAS bf16x8*)(vT + (n * 16 + l15) * AS + ks * 32 + q * 8);
;                     acc[n] = __builtin_amdgcn_mfma_f32_16x16x32_bf16(a, b, acc[n], 0, 0, 0);
;                 }
;             }
.Lmy_gpn_skip:
	s_or_b64 exec, exec, s[8:9]
	v_add_u32_e32 v134, s2, v1
	v_add_u32_e32 v134, s58, v134
	v_mov_b32_e32 v135, 0
	v_lshlrev_b64 v[136:137], 11, v[134:135]
	v_lshl_add_u64 v[136:137], v[36:37], 0, v[136:137]
	global_load_ushort v100, v[136:137], off offset:1024
	v_lshl_add_u64 v[138:139], v[136:137], 0, s[56:57]
	global_load_ushort v101, v[138:139], off offset:1024
	v_lshl_add_u64 v[136:137], v[138:139], 0, s[56:57]
	global_load_ushort v102, v[136:137], off offset:1024
	v_lshl_add_u64 v[138:139], v[136:137], 0, s[56:57]
	global_load_ushort v103, v[138:139], off offset:1024
	v_lshl_add_u64 v[136:137], v[138:139], 0, s[56:57]
	global_load_ushort v104, v[136:137], off offset:1024
	v_lshl_add_u64 v[138:139], v[136:137], 0, s[56:57]
	global_load_ushort v105, v[138:139], off offset:1024
	v_lshl_add_u64 v[136:137], v[138:139], 0, s[56:57]
	global_load_ushort v106, v[136:137], off offset:1024
	v_lshl_add_u64 v[138:139], v[136:137], 0, s[56:57]
	global_load_ushort v107, v[138:139], off offset:1024
	v_lshl_add_u64 v[136:137], v[138:139], 0, s[56:57]
	global_load_ushort v108, v[136:137], off offset:1024
	v_lshl_add_u64 v[138:139], v[136:137], 0, s[56:57]
	global_load_ushort v109, v[138:139], off offset:1024
	v_lshl_add_u64 v[136:137], v[138:139], 0, s[56:57]
	global_load_ushort v110, v[136:137], off offset:1024
	v_lshl_add_u64 v[138:139], v[136:137], 0, s[56:57]
	global_load_ushort v111, v[138:139], off offset:1024
	v_lshl_add_u64 v[136:137], v[138:139], 0, s[56:57]
	global_load_ushort v112, v[136:137], off offset:1024
	v_lshl_add_u64 v[138:139], v[136:137], 0, s[56:57]
	global_load_ushort v113, v[138:139], off offset:1024
	v_lshl_add_u64 v[136:137], v[138:139], 0, s[56:57]
	global_load_ushort v114, v[136:137], off offset:1024
	v_lshl_add_u64 v[138:139], v[136:137], 0, s[56:57]
	global_load_ushort v115, v[138:139], off offset:1024
	ds_read_b128 v[6:9], v24
	ds_read_b128 v[10:13], v50 offset:34816
	s_waitcnt lgkmcnt(0)
	v_mfma_f32_16x16x32_bf16 v[18:21], v[6:9], v[10:13], 0
	ds_read_b128 v[10:13], v50 offset:39168
	ds_read_b128 v[68:71], v50 offset:43520
	ds_read_b128 v[72:75], v50 offset:47872
	s_waitcnt lgkmcnt(2)
	v_mfma_f32_16x16x32_bf16 v[14:17], v[6:9], v[10:13], 0
	s_waitcnt lgkmcnt(1)
	v_mfma_f32_16x16x32_bf16 v[10:13], v[6:9], v[68:71], 0
	s_waitcnt lgkmcnt(0)
	v_mfma_f32_16x16x32_bf16 v[6:9], v[6:9], v[72:75], 0
	s_cbranch_vccnz .LBB0_943
	ds_read_b128 v[68:71], v24 offset:64
	ds_read_b128 v[72:75], v50 offset:34880
	s_andn2_b64 vcc, exec, s[12:13]
	s_waitcnt lgkmcnt(0)
	v_mfma_f32_16x16x32_bf16 v[18:21], v[68:71], v[72:75], v[18:21]
	ds_read_b128 v[72:75], v50 offset:39232
	ds_read_b128 v[76:79], v50 offset:43584
	s_waitcnt lgkmcnt(1)
	v_mfma_f32_16x16x32_bf16 v[14:17], v[68:71], v[72:75], v[14:17]
	ds_read_b128 v[72:75], v50 offset:47936
	s_waitcnt lgkmcnt(1)
	v_mfma_f32_16x16x32_bf16 v[10:13], v[68:71], v[76:79], v[10:13]
	s_waitcnt lgkmcnt(0)
	v_mfma_f32_16x16x32_bf16 v[6:9], v[68:71], v[72:75], v[6:9]
	s_cbranch_vccnz .LBB0_943
	ds_read_b128 v[68:71], v24 offset:128
	ds_read_b128 v[72:75], v50 offset:34944
	s_andn2_b64 vcc, exec, s[16:17]
	s_waitcnt lgkmcnt(0)
	v_mfma_f32_16x16x32_bf16 v[18:21], v[68:71], v[72:75], v[18:21]
	ds_read_b128 v[72:75], v50 offset:39296
	ds_read_b128 v[76:79], v50 offset:43648
	s_waitcnt lgkmcnt(1)
	v_mfma_f32_16x16x32_bf16 v[14:17], v[68:71], v[72:75], v[14:17]
	ds_read_b128 v[72:75], v50 offset:48000
	s_waitcnt lgkmcnt(1)
	v_mfma_f32_16x16x32_bf16 v[10:13], v[68:71], v[76:79], v[10:13]
	s_waitcnt lgkmcnt(0)
	v_mfma_f32_16x16x32_bf16 v[6:9], v[68:71], v[72:75], v[6:9]
	s_cbranch_vccnz .LBB0_943
	ds_read_b128 v[68:71], v24 offset:192
	ds_read_b128 v[72:75], v50 offset:35008
	s_waitcnt lgkmcnt(0)
	v_mfma_f32_16x16x32_bf16 v[18:21], v[68:71], v[72:75], v[18:21]
	ds_read_b128 v[72:75], v50 offset:39360
	ds_read_b128 v[76:79], v50 offset:43712
	s_waitcnt lgkmcnt(1)
	v_mfma_f32_16x16x32_bf16 v[14:17], v[68:71], v[72:75], v[14:17]
	ds_read_b128 v[72:75], v50 offset:48064
	s_waitcnt lgkmcnt(1)
	v_mfma_f32_16x16x32_bf16 v[10:13], v[68:71], v[76:79], v[10:13]
	s_waitcnt lgkmcnt(0)
	v_mfma_f32_16x16x32_bf16 v[6:9], v[68:71], v[72:75], v[6:9]
	s_branch .LBB0_943
